# static per-XCD decode assignment keyed on blockIdx bit 5 instead of bit 3 (different CU spread of the streaming workgroups)
# speedup vs baseline: 1.0097x; 1.0097x over previous
.LBB0_785:
	s_cmp_lt_i32 s96, 5
	s_cselect_b64 s[4:5], -1, 0
	s_cmp_gt_i32 s97, 4
	s_cselect_b64 s[6:7], -1, 0
	s_and_b64 s[4:5], s[4:5], s[6:7]
	s_andn2_b64 vcc, exec, s[4:5]
	s_cbranch_vccnz .LBB0_1063
	s_lshr_b32 s101, s2, 6
	s_lshl_b32 s101, s101, 5
	s_and_b32 s100, s2, 0x1f
	s_or_b32 s101, s101, s100
	s_bitcmp0_b32 s2, 5
	s_cselect_b32 s100, s101, 0x80
	s_and_b32 s10, s95, 0xffffffc0
	s_bfe_u32 s8, s95, 0x10006
	s_add_u32 s30, s38, 0x12300000
	s_addc_u32 s31, s39, 0
	s_mov_b32 s5, 0
	s_add_u32 s52, s38, 0x100000
	s_mul_i32 s4, s92, 0x60
	s_addc_u32 s53, s39, 0
	s_lshl_b64 s[4:5], s[4:5], 1
	s_add_u32 s56, s30, s4
	s_addc_u32 s57, s31, s5
	s_ashr_i32 s11, s10, 31
	s_lshr_b32 s5, s95, 7
	s_cmpk_lt_u32 s95, 0x80
	s_cselect_b64 s[58:59], -1, 0
	s_lshl_b32 s14, s5, 13
	s_mul_i32 s9, s92, 0x1200
	s_add_i32 s84, 0, 0x22000
	s_mul_i32 s12, s8, 0x1200
	s_add_i32 s83, 0, 0x22900
	s_lshr_b32 s13, s95, 4
	s_and_b32 s15, s14, 0x7fffc000
	s_lshl_b32 s78, s8, 5
	s_add_i32 s45, s84, s9
	s_lshl_b32 s3, s92, 5
	s_add_i32 s76, s83, s12
	s_add_i32 s77, s15, 0
	s_and_b32 s79, s13, 8
	s_or_b32 s80, s78, 8
	s_or_b32 s81, s78, 16
	s_or_b32 s82, s78, 24
	s_add_i32 s83, s83, s9
	s_add_i32 s84, s84, s12
	s_add_u32 s60, s38, 0x10f00000
	s_addc_u32 s61, s39, 0
	s_add_u32 s54, s38, 0x12000000
	s_addc_u32 s55, s39, 0
	s_lshl_b32 s9, s92, 8
	s_add_i32 s88, s9, 0
	v_mbcnt_hi_u32_b32 v187, -1, v254
	s_add_i32 s85, s77, 0x17400
	s_add_i32 s86, s14, 0
	s_add_i32 s87, s88, 0x24400
	s_add_i32 s88, s88, 0x16000
	s_and_b32 s12, 64, s95
	v_writelane_b32 v255, s90, 6
	v_and_b32_e32 v1, 64, v187
	s_cmp_eq_u32 s8, 0
	v_writelane_b32 v255, s91, 7
	s_mul_i32 s4, s92, 0x250
	v_xor_b32_e32 v0, 32, v187
	v_add_u32_e32 v188, 64, v1
	s_cselect_b64 s[8:9], -1, 0
	s_cmp_lg_u32 s12, 0
	v_cmp_lt_i32_e32 vcc, v0, v188
	v_writelane_b32 v255, s95, 8
	s_cselect_b64 s[62:63], -1, 0
	s_add_i32 s90, s4, 0
	s_mul_i32 s4, s92, 0x410
	v_add_u32_e32 v186, s10, v187
	v_cndmask_b32_e32 v0, v187, v0, vcc
	s_lshl_b32 s5, s5, 8
	v_writelane_b32 v255, s92, 5
	s_add_i32 s92, s4, 0
	s_add_i32 s93, 0, 0x21140
	v_lshlrev_b32_e32 v189, 2, v0
	v_cmp_eq_u32_e64 s[6:7], 0, v186
	s_add_i32 s89, s5, 0
	s_lshl_b64 s[64:65], s[10:11], 2
	s_add_i32 s91, s10, 0x200
	s_addk_i32 s92, 0x4c00
	v_mov_b32_e32 v121, 0
	s_mov_b32 s94, 0x8000
	s_movk_i32 s95, 0x600
	s_movk_i32 s96, 0x7fff
	s_movk_i32 s97, 0x50
	s_movk_i32 s50, 0x4000
	s_movk_i32 s51, 0x2000
	s_movk_i32 s4, 0x6000
	s_mov_b32 s5, 0xa000
	s_mov_b32 s48, 0xc000
	s_mov_b32 s49, 0xe000
	s_mov_b32 s74, 0x41000000
	s_lshl_b64 s[66:67], s[10:11], 1
	s_mov_b64 s[68:69], 0x19700400
	s_mov_b32 s75, 0x19700000
	v_mov_b32_e32 v123, s93
	v_mov_b32_e32 v138, 0xff800000
	s_branch .LBB0_789
